# v92 + no store drain (vmcnt) in front of the B2 scan: decode-state stores complete under the first input loads
# baseline (speedup 1.0000x reference)
.Lb2_u_loop:
	s_waitcnt lgkmcnt(0)
	s_barrier
	s_and_b32 s20, s22, 7
	s_lshl_b32 s20, s20, 3
	s_lshr_b32 s21, s22, 5
	s_add_i32 s20, s20, s21
	s_bfe_u32 s33, s22, 0x20003
	s_mul_i32 s28, s20, 0x300000
	s_add_u32 s28, s28, 0xcf90000
	s_add_u32 s28, s94, s28
	s_addc_u32 s29, s95, 0
	v_readfirstlane_b32 s21, v133
	s_cmpk_lt_u32 s21, 0x100
	s_cbranch_scc0 .Lb2_loader
	v_lshrrev_b32_e32 v112, 4, v133
	v_and_b32_e32 v113, 15, v133
	v_lshlrev_b32_e32 v8, 4, v113
	s_lshl_b32 s21, s33, 4
	s_addk_i32 s21, 0x140
	v_add_u32_e32 v9, s21, v112
	v_lshlrev_b32_e32 v9, 2, v9
	v_lshlrev_b32_e32 v10, 6, v112
	v_lshl_add_u32 v10, v113, 2, v10
	v_add_u32_e32 v10, 0xc000, v10
	v_lshlrev_b32_e32 v11, 8, v112
	v_lshl_add_u32 v11, v113, 4, v11
	s_lshl_b32 s21, s76, 6
	s_add_i32 s21, s21, s20
	s_lshl_b32 s21, s21, 14
	s_lshl_b32 s23, s33, 12
	s_add_i32 s21, s21, s23
	s_add_u32 s21, s21, 0x412c000
	s_add_u32 s40, s92, s21
	s_addc_u32 s41, s93, 0
	v_mov_b32_e32 v0, 0
	v_mov_b32_e32 v1, 0
	v_mov_b32_e32 v2, 0
	v_mov_b32_e32 v3, 0
	s_movk_i32 s34, 0x40
	s_setprio 2
	s_barrier
	ds_read_b128 v[12:15], v8 offset:0
	ds_read_b128 v[16:19], v8 offset:256
	ds_read_b128 v[20:23], v8 offset:512
	ds_read_b128 v[24:27], v8 offset:768
	ds_read_b128 v[28:31], v8 offset:1024
	ds_read_b32 v32, v9 offset:0
	ds_read_b128 v[36:39], v8 offset:1536
	ds_read_b128 v[40:43], v8 offset:1792
	ds_read_b128 v[44:47], v8 offset:2048
	ds_read_b128 v[48:51], v8 offset:2304
	ds_read_b128 v[52:55], v8 offset:2560
	ds_read_b32 v56, v9 offset:1536
	ds_read_b128 v[68:71], v8 offset:3072
	ds_read_b128 v[72:75], v8 offset:3328
	ds_read_b128 v[76:79], v8 offset:3584
	ds_read_b128 v[80:83], v8 offset:3840
	ds_read_b128 v[84:87], v8 offset:4096
	ds_read_b32 v88, v9 offset:3072
	s_waitcnt lgkmcnt(0)
